# grid barrier: the XCC leaders also issue their acquire right behind their write-back (before the cross-XCC wait) and no longer drain before releasing their local workgroups
# speedup vs baseline: 1.0097x; 1.0025x over previous
.LBB0_127:
	s_andn2_saveexec_b64 s[4:5], s[4:5]
	s_cbranch_execz .LBB0_147
	s_mov_b64 s[4:5], exec
	buffer_wbl2 sc1
	s_waitcnt lgkmcnt(0)
	s_waitcnt vmcnt(0)
	buffer_inv sc1
	v_mbcnt_lo_u32_b32 v1, s4, 0
	v_mbcnt_hi_u32_b32 v1, s5, v1
	v_cmp_eq_u32_e32 vcc, 0, v1
	s_and_saveexec_b64 s[6:7], vcc
	s_cbranch_execz .LBB0_130
	s_bcnt1_i32_b64 s3, s[4:5]
	v_readlane_b32 s4, v254, 50
	v_mov_b32_e32 v2, 0
	v_mov_b32_e32 v3, s3
	v_readlane_b32 s5, v254, 51
	s_nop 4
	global_atomic_add v2, v2, v3, s[4:5] sc0

.LBB0_144:
	s_or_b64 exec, exec, s[4:5]
	s_mov_b64 s[4:5], exec
	v_mbcnt_lo_u32_b32 v0, s4, 0
	v_mbcnt_hi_u32_b32 v0, s5, v0
	v_cmp_eq_u32_e32 vcc, 0, v0
	s_nop 0
	s_nop 0
	s_and_saveexec_b64 s[6:7], vcc
	s_cbranch_execz .LBB0_146
	s_bcnt1_i32_b64 s3, s[4:5]
	v_mov_b32_e32 v0, 0
	v_mov_b32_e32 v1, s3
	global_atomic_add v0, v1, s[20:21]

.LBB0_412:
	s_andn2_saveexec_b64 s[4:5], s[4:5]
	s_cbranch_execz .LBB0_432
	s_mov_b64 s[6:7], exec
	buffer_wbl2 sc1
	s_waitcnt lgkmcnt(0)
	s_waitcnt vmcnt(0)
	buffer_inv sc1
	v_mbcnt_lo_u32_b32 v1, s6, 0
	v_mbcnt_hi_u32_b32 v1, s7, v1
	v_cmp_eq_u32_e32 vcc, 0, v1
	s_and_saveexec_b64 s[12:13], vcc
	s_cbranch_execz .LBB0_415
	s_bcnt1_i32_b64 s6, s[6:7]
	v_mov_b32_e32 v3, s6
	v_readlane_b32 s6, v254, 50
	v_mov_b32_e32 v2, 0
	v_readlane_b32 s7, v254, 51
	s_nop 4
	global_atomic_add v2, v2, v3, s[6:7] sc0

.LBB0_429:
	s_or_b64 exec, exec, s[6:7]
	s_mov_b64 s[6:7], exec
	v_mbcnt_lo_u32_b32 v0, s6, 0
	v_mbcnt_hi_u32_b32 v0, s7, v0
	v_cmp_eq_u32_e32 vcc, 0, v0
	s_nop 0
	s_nop 0
	s_and_saveexec_b64 s[12:13], vcc
	s_cbranch_execz .LBB0_431
	s_bcnt1_i32_b64 s6, s[6:7]
	v_mov_b32_e32 v1, s6
	v_readlane_b32 s6, v255, 0
	v_mov_b32_e32 v0, 0
	v_readlane_b32 s7, v255, 1
	s_nop 4
	global_atomic_add v0, v1, s[6:7]

.LBB0_559:
	s_andn2_saveexec_b64 s[4:5], s[4:5]
	s_cbranch_execz .LBB0_579
	s_mov_b64 s[6:7], exec
	buffer_wbl2 sc1
	s_waitcnt lgkmcnt(0)
	s_waitcnt vmcnt(0)
	buffer_inv sc1
	v_mbcnt_lo_u32_b32 v1, s6, 0
	v_mbcnt_hi_u32_b32 v1, s7, v1
	v_cmp_eq_u32_e32 vcc, 0, v1
	s_and_saveexec_b64 s[10:11], vcc
	s_cbranch_execz .LBB0_562
	s_bcnt1_i32_b64 s6, s[6:7]
	v_mov_b32_e32 v3, s6
	v_readlane_b32 s6, v254, 50
	v_mov_b32_e32 v2, 0
	v_readlane_b32 s7, v254, 51
	s_nop 4
	global_atomic_add v2, v2, v3, s[6:7] sc0

.LBB0_576:
	s_or_b64 exec, exec, s[6:7]
	s_mov_b64 s[6:7], exec
	v_mbcnt_lo_u32_b32 v0, s6, 0
	v_mbcnt_hi_u32_b32 v0, s7, v0
	v_cmp_eq_u32_e32 vcc, 0, v0
	s_nop 0
	s_nop 0
	s_and_saveexec_b64 s[10:11], vcc
	s_cbranch_execz .LBB0_578
	s_bcnt1_i32_b64 s6, s[6:7]
	v_mov_b32_e32 v1, s6
	v_readlane_b32 s6, v255, 0
	v_mov_b32_e32 v0, 0
	v_readlane_b32 s7, v255, 1
	s_nop 4
	global_atomic_add v0, v1, s[6:7]

.LBB0_652:
	s_andn2_saveexec_b64 s[4:5], s[4:5]
	s_cbranch_execz .LBB0_672
	s_mov_b64 s[6:7], exec
	buffer_wbl2 sc1
	s_waitcnt lgkmcnt(0)
	s_waitcnt vmcnt(0)
	buffer_inv sc1
	v_mbcnt_lo_u32_b32 v1, s6, 0
	v_mbcnt_hi_u32_b32 v1, s7, v1
	v_cmp_eq_u32_e32 vcc, 0, v1
	s_and_saveexec_b64 s[10:11], vcc
	s_cbranch_execz .LBB0_655
	s_bcnt1_i32_b64 s2, s[6:7]
	v_readlane_b32 s6, v254, 50
	v_mov_b32_e32 v2, 0
	v_mov_b32_e32 v3, s2
	v_readlane_b32 s7, v254, 51
	s_nop 4
	global_atomic_add v2, v2, v3, s[6:7] sc0

.LBB0_669:
	s_or_b64 exec, exec, s[6:7]
	s_mov_b64 s[6:7], exec
	v_mbcnt_lo_u32_b32 v0, s6, 0
	v_mbcnt_hi_u32_b32 v0, s7, v0
	v_cmp_eq_u32_e32 vcc, 0, v0
	s_nop 0
	s_nop 0
	s_and_saveexec_b64 s[10:11], vcc
	s_cbranch_execz .LBB0_671
	s_bcnt1_i32_b64 s2, s[6:7]
	v_readlane_b32 s6, v255, 0
	v_mov_b32_e32 v0, 0
	v_mov_b32_e32 v1, s2
	v_readlane_b32 s7, v255, 1
	s_nop 4
	global_atomic_add v0, v1, s[6:7]

.LBB0_725:
	s_andn2_saveexec_b64 s[6:7], s[6:7]
	s_cbranch_execz .LBB0_745
	s_mov_b64 s[10:11], exec
	buffer_wbl2 sc1
	s_waitcnt lgkmcnt(0)
	s_waitcnt vmcnt(0)
	buffer_inv sc1
	v_mbcnt_lo_u32_b32 v1, s10, 0
	v_mbcnt_hi_u32_b32 v1, s11, v1
	v_cmp_eq_u32_e32 vcc, 0, v1
	s_and_saveexec_b64 s[12:13], vcc
	s_cbranch_execz .LBB0_728
	s_bcnt1_i32_b64 s2, s[10:11]
	v_readlane_b32 s10, v254, 50
	v_mov_b32_e32 v2, 0
	v_mov_b32_e32 v3, s2
	v_readlane_b32 s11, v254, 51
	s_nop 4
	global_atomic_add v2, v2, v3, s[10:11] sc0

.LBB0_742:
	s_or_b64 exec, exec, s[10:11]
	s_mov_b64 s[10:11], exec
	v_mbcnt_lo_u32_b32 v0, s10, 0
	v_mbcnt_hi_u32_b32 v0, s11, v0
	v_cmp_eq_u32_e32 vcc, 0, v0
	s_nop 0
	s_nop 0
	s_and_saveexec_b64 s[12:13], vcc
	s_cbranch_execz .LBB0_744
	s_bcnt1_i32_b64 s2, s[10:11]
	v_mov_b32_e32 v0, 0
	v_mov_b32_e32 v1, s2
	global_atomic_add v0, v1, s[34:35]

.LBB0_833:
	s_or_b64 exec, exec, s[6:7]
	s_mov_b64 s[6:7], exec
	v_mbcnt_lo_u32_b32 v0, s6, 0
	v_mbcnt_hi_u32_b32 v0, s7, v0
	v_cmp_eq_u32_e32 vcc, 0, v0
	s_nop 0
	s_nop 0
	s_and_saveexec_b64 s[10:11], vcc
	s_cbranch_execz .LBB0_835
	s_bcnt1_i32_b64 s2, s[6:7]
	v_mov_b32_e32 v0, 0
	v_mov_b32_e32 v1, s2
	global_atomic_add v0, v1, s[34:35]

.LBB0_900:
	s_andn2_saveexec_b64 s[4:5], s[4:5]
	s_cbranch_execz .LBB0_920
	s_mov_b64 s[4:5], exec
	buffer_wbl2 sc1
	s_waitcnt lgkmcnt(0)
	s_waitcnt vmcnt(0)
	buffer_inv sc1
	v_mbcnt_lo_u32_b32 v1, s4, 0
	v_mbcnt_hi_u32_b32 v1, s5, v1
	v_cmp_eq_u32_e32 vcc, 0, v1
	s_and_saveexec_b64 s[6:7], vcc
	s_cbranch_execz .LBB0_903
	s_bcnt1_i32_b64 s2, s[4:5]
	v_readlane_b32 s4, v254, 50
	v_mov_b32_e32 v2, 0
	v_mov_b32_e32 v3, s2
	v_readlane_b32 s5, v254, 51
	s_nop 4
	global_atomic_add v2, v2, v3, s[4:5] sc0

.LBB0_917:
	s_or_b64 exec, exec, s[4:5]
	s_mov_b64 s[4:5], exec
	v_mbcnt_lo_u32_b32 v0, s4, 0
	v_mbcnt_hi_u32_b32 v0, s5, v0
	v_cmp_eq_u32_e32 vcc, 0, v0
	s_nop 0
	s_nop 0
	s_and_saveexec_b64 s[6:7], vcc
	s_cbranch_execz .LBB0_919
	s_bcnt1_i32_b64 s2, s[4:5]
	v_mov_b32_e32 v0, 0
	v_mov_b32_e32 v1, s2
	global_atomic_add v0, v1, s[34:35]
